# GEMM K-loop (modes 0/2): register-staged LDS writes and next-tile loads spread over three MFMA groups instead of two
# baseline (speedup 1.0000x reference)
; #define G5_LOAD(k0)                                                                 \
;   {                                                                                 \
;     _Pragma("unroll") for (int i_ = 0; i_ < 4; ++i_) ra[i_] = ldg16(Ap + (size_t)(i_ * 64) * lda + (k0)); \
;     _Pragma("unroll") for (int i_ = 0; i_ < 4; ++i_) rb[i_] = ldg16(Bp + (size_t)(i_ * 64) * ldb + (k0)); \
;   }
; #define G5_STORE(s)                                                                 \
;   {                                                                                 \
;     _Pragma("unroll") for (int i_ = 0; i_ < 4; ++i_) *(u32x4*)(Sw + (s) * STG + i_ * 64 * GS) = ra[i_]; \
;     _Pragma("unroll") for (int i_ = 0; i_ < 4; ++i_) *(u32x4*)(Sw + (s) * STG + 256 * GS + i_ * 64 * GS) = rb[i_]; \
;   }
; template <typename Epi>
; DI void gemm_tile512(const u16* __restrict__ A, int lda, const u16* __restrict__ Bt, int ldb, int K, char* lds_all, Epi epi) {
;     ...
;   const int nk = K >> 6;
;   __syncthreads();
;   G5_LOAD(0);
;   G5_STORE(0);
;   G5_LOAD(64);
;   __syncthreads();
;   for (int kt = 0; kt + 2 < nk; ++kt) {
;     const int cur = kt & 1;
;     G5_COMPUTE(cur);
;     G5_STORE(cur ^ 1);
;     G5_LOAD((kt + 2) << 6);
;     __syncthreads();
;   }
.Lg3_k_m0:
	s_barrier
	ds_read_b128 v[194:197], v179 offset:36864
	ds_read_b128 v[166:169], v178
	ds_read_b128 v[198:201], v179 offset:41472
	ds_read_b128 v[170:173], v178 offset:4608
	ds_read_b128 v[174:177], v178 offset:9216
	ds_read_b128 v[190:193], v178 offset:13824
	s_waitcnt lgkmcnt(4)
	v_mfma_f32_32x32x16_bf16 v[114:129], v[194:197], v[166:169], 0
	ds_read_b128 v[234:237], v179 offset:36896
	s_waitcnt lgkmcnt(4)
	v_mfma_f32_32x32x16_bf16 v[98:113], v[198:201], v[166:169], 0
	ds_read_b128 v[218:221], v178 offset:32
	s_waitcnt lgkmcnt(4)
	v_mfma_f32_32x32x16_bf16 v[82:97], v[194:197], v[170:173], 0
	ds_read_b128 v[202:205], v179 offset:41504
	v_mfma_f32_32x32x16_bf16 v[66:81], v[198:201], v[170:173], 0
	ds_read_b128 v[222:225], v178 offset:4640
	global_load_dwordx4 v[130:133], v206, s[98:99]
	s_waitcnt lgkmcnt(5)
	v_mfma_f32_32x32x16_bf16 v[50:65], v[194:197], v[174:177], 0
	ds_read_b128 v[226:229], v178 offset:9248
	v_mfma_f32_32x32x16_bf16 v[34:49], v[198:201], v[174:177], 0
	ds_read_b128 v[230:233], v178 offset:13856
	s_waitcnt lgkmcnt(6)
	v_mfma_f32_32x32x16_bf16 v[18:33], v[194:197], v[190:193], 0
	v_mfma_f32_32x32x16_bf16 v[2:17], v[198:201], v[190:193], 0
	global_load_dwordx4 v[134:137], v207, s[98:99]
	s_waitcnt lgkmcnt(4)
	v_mfma_f32_32x32x16_bf16 v[114:129], v[234:237], v[218:221], v[114:129]
	ds_read_b128 v[194:197], v179 offset:36928
	s_waitcnt lgkmcnt(4)
	v_mfma_f32_32x32x16_bf16 v[98:113], v[202:205], v[218:221], v[98:113]
	ds_read_b128 v[166:169], v178 offset:64
	s_waitcnt lgkmcnt(4)
	v_mfma_f32_32x32x16_bf16 v[82:97], v[234:237], v[222:225], v[82:97]
	ds_read_b128 v[198:201], v179 offset:41536
	v_mfma_f32_32x32x16_bf16 v[66:81], v[202:205], v[222:225], v[66:81]
	ds_read_b128 v[170:173], v178 offset:4672
	global_load_dwordx4 v[138:141], v208, s[98:99]
	s_waitcnt lgkmcnt(5)
	v_mfma_f32_32x32x16_bf16 v[50:65], v[234:237], v[226:229], v[50:65]
	ds_read_b128 v[174:177], v178 offset:9280
	v_mfma_f32_32x32x16_bf16 v[34:49], v[202:205], v[226:229], v[34:49]
	ds_read_b128 v[190:193], v178 offset:13888
	s_waitcnt lgkmcnt(6)
	v_mfma_f32_32x32x16_bf16 v[18:33], v[234:237], v[230:233], v[18:33]
	v_mfma_f32_32x32x16_bf16 v[2:17], v[202:205], v[230:233], v[2:17]
	global_load_dwordx4 v[142:145], v238, s[98:99]
	s_waitcnt lgkmcnt(4)
	v_mfma_f32_32x32x16_bf16 v[114:129], v[194:197], v[166:169], v[114:129]
	ds_read_b128 v[234:237], v179 offset:36960
	s_waitcnt lgkmcnt(4)
	v_mfma_f32_32x32x16_bf16 v[98:113], v[198:201], v[166:169], v[98:113]
	ds_read_b128 v[218:221], v178 offset:96
	global_load_dwordx4 v[146:149], v206, s[100:101]
	s_waitcnt lgkmcnt(4)
	v_mfma_f32_32x32x16_bf16 v[82:97], v[194:197], v[170:173], v[82:97]
	ds_read_b128 v[202:205], v179 offset:41568
	v_mfma_f32_32x32x16_bf16 v[66:81], v[198:201], v[170:173], v[66:81]
	ds_read_b128 v[222:225], v178 offset:4704
	global_load_dwordx4 v[150:153], v207, s[100:101]
	s_waitcnt lgkmcnt(5)
	v_mfma_f32_32x32x16_bf16 v[50:65], v[194:197], v[174:177], v[50:65]
	ds_read_b128 v[226:229], v178 offset:9312
	v_mfma_f32_32x32x16_bf16 v[34:49], v[198:201], v[174:177], v[34:49]
	ds_read_b128 v[230:233], v178 offset:13920
	global_load_dwordx4 v[154:157], v208, s[100:101]
	v_add_u32_e32 v178, s12, v178
	v_add_u32_e32 v179, s12, v179
	s_waitcnt lgkmcnt(6)
	v_mfma_f32_32x32x16_bf16 v[18:33], v[194:197], v[190:193], v[18:33]
	v_mfma_f32_32x32x16_bf16 v[2:17], v[198:201], v[190:193], v[2:17]
	global_load_dwordx4 v[158:161], v238, s[100:101]
	v_subrev_u32_e32 v180, s12, v180
	s_sub_u32 s12, 0, s12
	s_add_u32 s98, s98, 0x80
	s_addc_u32 s99, s99, 0
	s_add_u32 s100, s100, 0x80
	s_addc_u32 s101, s101, 0
	s_waitcnt lgkmcnt(0)
.Lg3_loop_m0:
	s_barrier
	ds_read_b128 v[194:197], v179 offset:36864
	ds_read_b128 v[166:169], v178
	v_mfma_f32_32x32x16_bf16 v[114:129], v[234:237], v[218:221], v[114:129]
	ds_read_b128 v[198:201], v179 offset:41472
	v_mfma_f32_32x32x16_bf16 v[98:113], v[202:205], v[218:221], v[98:113]
	ds_read_b128 v[170:173], v178 offset:4608
	v_mfma_f32_32x32x16_bf16 v[82:97], v[234:237], v[222:225], v[82:97]
	ds_read_b128 v[174:177], v178 offset:9216
	v_mfma_f32_32x32x16_bf16 v[66:81], v[202:205], v[222:225], v[66:81]
	ds_read_b128 v[190:193], v178 offset:13824
	v_mfma_f32_32x32x16_bf16 v[50:65], v[234:237], v[226:229], v[50:65]
	v_mfma_f32_32x32x16_bf16 v[34:49], v[202:205], v[226:229], v[34:49]
	v_mfma_f32_32x32x16_bf16 v[18:33], v[234:237], v[230:233], v[18:33]
	v_mfma_f32_32x32x16_bf16 v[2:17], v[202:205], v[230:233], v[2:17]
	s_waitcnt lgkmcnt(4)
	v_mfma_f32_32x32x16_bf16 v[114:129], v[194:197], v[166:169], v[114:129]
	ds_read_b128 v[234:237], v179 offset:36896
	s_waitcnt lgkmcnt(4)
	v_mfma_f32_32x32x16_bf16 v[98:113], v[198:201], v[166:169], v[98:113]
	ds_read_b128 v[218:221], v178 offset:32
	s_waitcnt lgkmcnt(4)
	v_mfma_f32_32x32x16_bf16 v[82:97], v[194:197], v[170:173], v[82:97]
	ds_read_b128 v[202:205], v179 offset:41504
	v_mfma_f32_32x32x16_bf16 v[66:81], v[198:201], v[170:173], v[66:81]
	ds_read_b128 v[222:225], v178 offset:4640
	s_waitcnt vmcnt(7)
	ds_write_b128 v180, v[130:133]
	global_load_dwordx4 v[130:133], v206, s[98:99]
	s_waitcnt lgkmcnt(6)
	v_mfma_f32_32x32x16_bf16 v[50:65], v[194:197], v[174:177], v[50:65]
	ds_read_b128 v[226:229], v178 offset:9248
	v_mfma_f32_32x32x16_bf16 v[34:49], v[198:201], v[174:177], v[34:49]
	ds_read_b128 v[230:233], v178 offset:13856
	s_waitcnt lgkmcnt(7)
	v_mfma_f32_32x32x16_bf16 v[18:33], v[194:197], v[190:193], v[18:33]
	v_mfma_f32_32x32x16_bf16 v[2:17], v[198:201], v[190:193], v[2:17]
	s_waitcnt vmcnt(7)
	ds_write_b128 v180, v[134:137] offset:9216
	global_load_dwordx4 v[134:137], v207, s[98:99]
	s_waitcnt lgkmcnt(6)
; #define G5_LOAD(k0)                                                                 \
;   {                                                                                 \
;     _Pragma("unroll") for (int i_ = 0; i_ < 4; ++i_) ra[i_] = ldg16(Ap + (size_t)(i_ * 64) * lda + (k0)); \
;     _Pragma("unroll") for (int i_ = 0; i_ < 4; ++i_) rb[i_] = ldg16(Bp + (size_t)(i_ * 64) * ldb + (k0)); \
;   }
; #define G5_STORE(s)                                                                 \
;   {                                                                                 \
;     _Pragma("unroll") for (int i_ = 0; i_ < 4; ++i_) *(u32x4*)(Sw + (s) * STG + i_ * 64 * GS) = ra[i_]; \
;     _Pragma("unroll") for (int i_ = 0; i_ < 4; ++i_) *(u32x4*)(Sw + (s) * STG + 256 * GS + i_ * 64 * GS) = rb[i_]; \
;   }
; template <typename Epi>
; DI void gemm_tile512(const u16* __restrict__ A, int lda, const u16* __restrict__ Bt, int ldb, int K, char* lds_all, Epi epi) {
;     ...
;   const int nk = K >> 6;
;   __syncthreads();
;   G5_LOAD(0);
;   G5_STORE(0);
;   G5_LOAD(64);
;   __syncthreads();
;   for (int kt = 0; kt + 2 < nk; ++kt) {
;     const int cur = kt & 1;
;     G5_COMPUTE(cur);
;     G5_STORE(cur ^ 1);
;     G5_LOAD((kt + 2) << 6);
;     __syncthreads();
;   }
;   {
;     const int cur = (nk - 2) & 1;
;     G5_COMPUTE(cur);
;     G5_STORE(cur ^ 1);
;     __syncthreads();
;     G5_COMPUTE(cur ^ 1);
;   }
	v_mfma_f32_32x32x16_bf16 v[114:129], v[234:237], v[218:221], v[114:129]
	ds_read_b128 v[194:197], v179 offset:36928
	s_waitcnt lgkmcnt(6)
	v_mfma_f32_32x32x16_bf16 v[98:113], v[202:205], v[218:221], v[98:113]
	ds_read_b128 v[166:169], v178 offset:64
	s_waitcnt lgkmcnt(6)
	v_mfma_f32_32x32x16_bf16 v[82:97], v[234:237], v[222:225], v[82:97]
	ds_read_b128 v[198:201], v179 offset:41536
	v_mfma_f32_32x32x16_bf16 v[66:81], v[202:205], v[222:225], v[66:81]
	ds_read_b128 v[170:173], v178 offset:4672
	s_waitcnt vmcnt(7)
	ds_write_b128 v180, v[138:141] offset:18432
	global_load_dwordx4 v[138:141], v208, s[98:99]
	s_waitcnt lgkmcnt(7)
	v_mfma_f32_32x32x16_bf16 v[50:65], v[234:237], v[226:229], v[50:65]
	ds_read_b128 v[174:177], v178 offset:9280
	v_mfma_f32_32x32x16_bf16 v[34:49], v[202:205], v[226:229], v[34:49]
	ds_read_b128 v[190:193], v178 offset:13888
	s_waitcnt lgkmcnt(8)
	v_mfma_f32_32x32x16_bf16 v[18:33], v[234:237], v[230:233], v[18:33]
	v_mfma_f32_32x32x16_bf16 v[2:17], v[202:205], v[230:233], v[2:17]
	s_waitcnt vmcnt(7)
	ds_write_b128 v180, v[142:145] offset:27648
	global_load_dwordx4 v[142:145], v238, s[98:99]
	s_waitcnt lgkmcnt(6)
	v_mfma_f32_32x32x16_bf16 v[114:129], v[194:197], v[166:169], v[114:129]
	ds_read_b128 v[234:237], v179 offset:36960
	s_waitcnt lgkmcnt(6)
	v_mfma_f32_32x32x16_bf16 v[98:113], v[198:201], v[166:169], v[98:113]
	ds_read_b128 v[218:221], v178 offset:96
	s_waitcnt vmcnt(7)
	ds_write_b128 v180, v[146:149] offset:36864
	global_load_dwordx4 v[146:149], v206, s[100:101]
	s_waitcnt lgkmcnt(7)
	v_mfma_f32_32x32x16_bf16 v[82:97], v[194:197], v[170:173], v[82:97]
	ds_read_b128 v[202:205], v179 offset:41568
	v_mfma_f32_32x32x16_bf16 v[66:81], v[198:201], v[170:173], v[66:81]
	ds_read_b128 v[222:225], v178 offset:4704
	s_waitcnt vmcnt(7)
	ds_write_b128 v180, v[150:153] offset:46080
	global_load_dwordx4 v[150:153], v207, s[100:101]
	s_waitcnt lgkmcnt(8)
	v_mfma_f32_32x32x16_bf16 v[50:65], v[194:197], v[174:177], v[50:65]
	ds_read_b128 v[226:229], v178 offset:9312
	v_mfma_f32_32x32x16_bf16 v[34:49], v[198:201], v[174:177], v[34:49]
	ds_read_b128 v[230:233], v178 offset:13920
	s_waitcnt vmcnt(7)
	ds_write_b128 v180, v[154:157] offset:55296
	global_load_dwordx4 v[154:157], v208, s[100:101]
	v_add_u32_e32 v178, s12, v178
	v_add_u32_e32 v179, s12, v179
	s_waitcnt lgkmcnt(10)
	v_mfma_f32_32x32x16_bf16 v[18:33], v[194:197], v[190:193], v[18:33]
	v_mfma_f32_32x32x16_bf16 v[2:17], v[198:201], v[190:193], v[2:17]
	s_waitcnt vmcnt(7)
	ds_write_b128 v180, v[158:161] offset:64512
	global_load_dwordx4 v[158:161], v238, s[100:101]
	v_subrev_u32_e32 v180, s12, v180
	s_sub_u32 s12, 0, s12
	s_add_u32 s98, s98, 0x80
	s_addc_u32 s99, s99, 0
	s_add_u32 s100, s100, 0x80
	s_addc_u32 s101, s101, 0
	s_waitcnt lgkmcnt(0)
	s_sub_u32 s13, s13, 1
	s_cmp_lg_u32 s13, 0
	s_cbranch_scc1 .Lg3_loop_m0
	s_barrier
	ds_read_b128 v[194:197], v179 offset:36864
	ds_read_b128 v[166:169], v178
	v_mfma_f32_32x32x16_bf16 v[114:129], v[234:237], v[218:221], v[114:129]
	ds_read_b128 v[198:201], v179 offset:41472
	v_mfma_f32_32x32x16_bf16 v[98:113], v[202:205], v[218:221], v[98:113]
	ds_read_b128 v[170:173], v178 offset:4608
	v_mfma_f32_32x32x16_bf16 v[82:97], v[234:237], v[222:225], v[82:97]
	ds_read_b128 v[174:177], v178 offset:9216
	v_mfma_f32_32x32x16_bf16 v[66:81], v[202:205], v[222:225], v[66:81]
	ds_read_b128 v[190:193], v178 offset:13824
	v_mfma_f32_32x32x16_bf16 v[50:65], v[234:237], v[226:229], v[50:65]
	v_mfma_f32_32x32x16_bf16 v[34:49], v[202:205], v[226:229], v[34:49]
	v_mfma_f32_32x32x16_bf16 v[18:33], v[234:237], v[230:233], v[18:33]
	v_mfma_f32_32x32x16_bf16 v[2:17], v[202:205], v[230:233], v[2:17]
	s_waitcnt lgkmcnt(4)
	v_mfma_f32_32x32x16_bf16 v[114:129], v[194:197], v[166:169], v[114:129]
	ds_read_b128 v[234:237], v179 offset:36896
	s_waitcnt lgkmcnt(4)
	v_mfma_f32_32x32x16_bf16 v[98:113], v[198:201], v[166:169], v[98:113]
	ds_read_b128 v[218:221], v178 offset:32
	s_waitcnt lgkmcnt(4)
	v_mfma_f32_32x32x16_bf16 v[82:97], v[194:197], v[170:173], v[82:97]
	ds_read_b128 v[202:205], v179 offset:41504
	v_mfma_f32_32x32x16_bf16 v[66:81], v[198:201], v[170:173], v[66:81]
	ds_read_b128 v[222:225], v178 offset:4640
	s_waitcnt vmcnt(7)
	ds_write_b128 v180, v[130:133]
	s_waitcnt lgkmcnt(6)
	v_mfma_f32_32x32x16_bf16 v[50:65], v[194:197], v[174:177], v[50:65]
	ds_read_b128 v[226:229], v178 offset:9248
	v_mfma_f32_32x32x16_bf16 v[34:49], v[198:201], v[174:177], v[34:49]
	ds_read_b128 v[230:233], v178 offset:13856
	s_waitcnt lgkmcnt(7)
	v_mfma_f32_32x32x16_bf16 v[18:33], v[194:197], v[190:193], v[18:33]
	v_mfma_f32_32x32x16_bf16 v[2:17], v[198:201], v[190:193], v[2:17]
	s_waitcnt vmcnt(6)
	ds_write_b128 v180, v[134:137] offset:9216
	s_waitcnt lgkmcnt(6)
	v_mfma_f32_32x32x16_bf16 v[114:129], v[234:237], v[218:221], v[114:129]
	ds_read_b128 v[194:197], v179 offset:36928
	s_waitcnt lgkmcnt(6)
	v_mfma_f32_32x32x16_bf16 v[98:113], v[202:205], v[218:221], v[98:113]
	ds_read_b128 v[166:169], v178 offset:64
	s_waitcnt lgkmcnt(6)
	v_mfma_f32_32x32x16_bf16 v[82:97], v[234:237], v[222:225], v[82:97]
	ds_read_b128 v[198:201], v179 offset:41536
	v_mfma_f32_32x32x16_bf16 v[66:81], v[202:205], v[222:225], v[66:81]
	ds_read_b128 v[170:173], v178 offset:4672
	s_waitcnt vmcnt(5)
	ds_write_b128 v180, v[138:141] offset:18432
	s_waitcnt lgkmcnt(7)
	v_mfma_f32_32x32x16_bf16 v[50:65], v[234:237], v[226:229], v[50:65]
	ds_read_b128 v[174:177], v178 offset:9280
	v_mfma_f32_32x32x16_bf16 v[34:49], v[202:205], v[226:229], v[34:49]
	ds_read_b128 v[190:193], v178 offset:13888
	s_waitcnt lgkmcnt(8)
	v_mfma_f32_32x32x16_bf16 v[18:33], v[234:237], v[230:233], v[18:33]
	v_mfma_f32_32x32x16_bf16 v[2:17], v[202:205], v[230:233], v[2:17]
	s_waitcnt vmcnt(4)
; #define G5_STORE(s)                                                                 \
;   {                                                                                 \
;     _Pragma("unroll") for (int i_ = 0; i_ < 4; ++i_) *(u32x4*)(Sw + (s) * STG + i_ * 64 * GS) = ra[i_]; \
;     _Pragma("unroll") for (int i_ = 0; i_ < 4; ++i_) *(u32x4*)(Sw + (s) * STG + 256 * GS + i_ * 64 * GS) = rb[i_]; \
;   }
; template <typename Epi>
; DI void gemm_tile512(const u16* __restrict__ A, int lda, const u16* __restrict__ Bt, int ldb, int K, char* lds_all, Epi epi) {
;     ...
;   {
;     const int cur = (nk - 2) & 1;
;     G5_COMPUTE(cur);
;     G5_STORE(cur ^ 1);
;     __syncthreads();
;     G5_COMPUTE(cur ^ 1);
;   }
; DI void gemm_phase(const Params& p, int layer, int mode, int nrows, char* lds_all) {
;     ...
;             if (n0 == C_BAB && c8 < 16) {
;               *(float4*)((float*)(p.ws + O_GRAW) + (size_t)row * 16 + c8) = v0;
;               *(float4*)((float*)(p.ws + O_GRAW) + (size_t)row * 16 + c8 + 4) = v1;
;             }
	ds_write_b128 v180, v[142:145] offset:27648
	s_waitcnt lgkmcnt(6)
	v_mfma_f32_32x32x16_bf16 v[114:129], v[194:197], v[166:169], v[114:129]
	ds_read_b128 v[234:237], v179 offset:36960
	s_waitcnt lgkmcnt(6)
	v_mfma_f32_32x32x16_bf16 v[98:113], v[198:201], v[166:169], v[98:113]
	ds_read_b128 v[218:221], v178 offset:96
	s_waitcnt vmcnt(3)
	ds_write_b128 v180, v[146:149] offset:36864
	s_waitcnt lgkmcnt(7)
	v_mfma_f32_32x32x16_bf16 v[82:97], v[194:197], v[170:173], v[82:97]
	ds_read_b128 v[202:205], v179 offset:41568
	v_mfma_f32_32x32x16_bf16 v[66:81], v[198:201], v[170:173], v[66:81]
	ds_read_b128 v[222:225], v178 offset:4704
	s_waitcnt vmcnt(2)
	ds_write_b128 v180, v[150:153] offset:46080
	s_waitcnt lgkmcnt(8)
	v_mfma_f32_32x32x16_bf16 v[50:65], v[194:197], v[174:177], v[50:65]
	ds_read_b128 v[226:229], v178 offset:9312
	v_mfma_f32_32x32x16_bf16 v[34:49], v[198:201], v[174:177], v[34:49]
	ds_read_b128 v[230:233], v178 offset:13920
	s_waitcnt vmcnt(1)
	ds_write_b128 v180, v[154:157] offset:55296
	v_add_u32_e32 v178, s12, v178
	v_add_u32_e32 v179, s12, v179
	s_waitcnt lgkmcnt(10)
	v_mfma_f32_32x32x16_bf16 v[18:33], v[194:197], v[190:193], v[18:33]
	v_mfma_f32_32x32x16_bf16 v[2:17], v[198:201], v[190:193], v[2:17]
	s_waitcnt vmcnt(0)
	ds_write_b128 v180, v[158:161] offset:64512
	v_subrev_u32_e32 v180, s12, v180
	s_sub_u32 s12, 0, s12
	s_add_u32 s98, s98, 0x80
	s_addc_u32 s99, s99, 0
	s_add_u32 s100, s100, 0x80
	s_addc_u32 s101, s101, 0
	s_waitcnt lgkmcnt(0)
	s_barrier
	ds_read_b128 v[194:197], v179 offset:36864
	ds_read_b128 v[166:169], v178
	v_mfma_f32_32x32x16_bf16 v[114:129], v[234:237], v[218:221], v[114:129]
	ds_read_b128 v[198:201], v179 offset:41472
	v_mfma_f32_32x32x16_bf16 v[98:113], v[202:205], v[218:221], v[98:113]
	ds_read_b128 v[170:173], v178 offset:4608
	v_mfma_f32_32x32x16_bf16 v[82:97], v[234:237], v[222:225], v[82:97]
	ds_read_b128 v[174:177], v178 offset:9216
	v_mfma_f32_32x32x16_bf16 v[66:81], v[202:205], v[222:225], v[66:81]
	ds_read_b128 v[190:193], v178 offset:13824
	v_mfma_f32_32x32x16_bf16 v[50:65], v[234:237], v[226:229], v[50:65]
	v_mfma_f32_32x32x16_bf16 v[34:49], v[202:205], v[226:229], v[34:49]
	v_mfma_f32_32x32x16_bf16 v[18:33], v[234:237], v[230:233], v[18:33]
	v_mfma_f32_32x32x16_bf16 v[2:17], v[202:205], v[230:233], v[2:17]
	s_waitcnt lgkmcnt(4)
	v_mfma_f32_32x32x16_bf16 v[114:129], v[194:197], v[166:169], v[114:129]
	ds_read_b128 v[234:237], v179 offset:36896
	s_waitcnt lgkmcnt(4)
	v_mfma_f32_32x32x16_bf16 v[98:113], v[198:201], v[166:169], v[98:113]
	ds_read_b128 v[218:221], v178 offset:32
	s_waitcnt lgkmcnt(4)
	v_mfma_f32_32x32x16_bf16 v[82:97], v[194:197], v[170:173], v[82:97]
	ds_read_b128 v[202:205], v179 offset:41504
	v_mfma_f32_32x32x16_bf16 v[66:81], v[198:201], v[170:173], v[66:81]
	ds_read_b128 v[222:225], v178 offset:4640
	s_waitcnt lgkmcnt(5)
	v_mfma_f32_32x32x16_bf16 v[50:65], v[194:197], v[174:177], v[50:65]
	ds_read_b128 v[226:229], v178 offset:9248
	v_mfma_f32_32x32x16_bf16 v[34:49], v[198:201], v[174:177], v[34:49]
	ds_read_b128 v[230:233], v178 offset:13856
	s_waitcnt lgkmcnt(6)
	v_mfma_f32_32x32x16_bf16 v[18:33], v[194:197], v[190:193], v[18:33]
	v_mfma_f32_32x32x16_bf16 v[2:17], v[198:201], v[190:193], v[2:17]
	s_waitcnt lgkmcnt(4)
	v_mfma_f32_32x32x16_bf16 v[114:129], v[234:237], v[218:221], v[114:129]
	ds_read_b128 v[194:197], v179 offset:36928
	s_waitcnt lgkmcnt(4)
	v_mfma_f32_32x32x16_bf16 v[98:113], v[202:205], v[218:221], v[98:113]
	ds_read_b128 v[166:169], v178 offset:64
	s_waitcnt lgkmcnt(4)
	v_mfma_f32_32x32x16_bf16 v[82:97], v[234:237], v[222:225], v[82:97]
	ds_read_b128 v[198:201], v179 offset:41536
	v_mfma_f32_32x32x16_bf16 v[66:81], v[202:205], v[222:225], v[66:81]
	ds_read_b128 v[170:173], v178 offset:4672
	s_waitcnt lgkmcnt(5)
	v_mfma_f32_32x32x16_bf16 v[50:65], v[234:237], v[226:229], v[50:65]
	ds_read_b128 v[174:177], v178 offset:9280
	v_mfma_f32_32x32x16_bf16 v[34:49], v[202:205], v[226:229], v[34:49]
	ds_read_b128 v[190:193], v178 offset:13888
	s_waitcnt lgkmcnt(6)
	v_mfma_f32_32x32x16_bf16 v[18:33], v[234:237], v[230:233], v[18:33]
	v_mfma_f32_32x32x16_bf16 v[2:17], v[202:205], v[230:233], v[2:17]
	s_waitcnt lgkmcnt(4)
	v_mfma_f32_32x32x16_bf16 v[114:129], v[194:197], v[166:169], v[114:129]
	ds_read_b128 v[234:237], v179 offset:36960
	s_waitcnt lgkmcnt(4)
	v_mfma_f32_32x32x16_bf16 v[98:113], v[198:201], v[166:169], v[98:113]
	ds_read_b128 v[218:221], v178 offset:96
	s_waitcnt lgkmcnt(4)
	v_mfma_f32_32x32x16_bf16 v[82:97], v[194:197], v[170:173], v[82:97]
	ds_read_b128 v[202:205], v179 offset:41568
	v_mfma_f32_32x32x16_bf16 v[66:81], v[198:201], v[170:173], v[66:81]
	ds_read_b128 v[222:225], v178 offset:4704
	s_waitcnt lgkmcnt(5)
	v_mfma_f32_32x32x16_bf16 v[50:65], v[194:197], v[174:177], v[50:65]
	ds_read_b128 v[226:229], v178 offset:9312
	v_mfma_f32_32x32x16_bf16 v[34:49], v[198:201], v[174:177], v[34:49]
	ds_read_b128 v[230:233], v178 offset:13920
	s_waitcnt lgkmcnt(6)
	v_mfma_f32_32x32x16_bf16 v[18:33], v[194:197], v[190:193], v[18:33]
	v_mfma_f32_32x32x16_bf16 v[2:17], v[198:201], v[190:193], v[2:17]
	s_waitcnt lgkmcnt(0)
	v_mfma_f32_32x32x16_bf16 v[114:129], v[234:237], v[218:221], v[114:129]
	v_mfma_f32_32x32x16_bf16 v[98:113], v[202:205], v[218:221], v[98:113]
	v_mfma_f32_32x32x16_bf16 v[82:97], v[234:237], v[222:225], v[82:97]
	v_mfma_f32_32x32x16_bf16 v[66:81], v[202:205], v[222:225], v[66:81]
	v_mfma_f32_32x32x16_bf16 v[50:65], v[234:237], v[226:229], v[50:65]
	v_mfma_f32_32x32x16_bf16 v[34:49], v[202:205], v[226:229], v[34:49]
	v_mfma_f32_32x32x16_bf16 v[18:33], v[234:237], v[230:233], v[18:33]
	v_mfma_f32_32x32x16_bf16 v[2:17], v[202:205], v[230:233], v[2:17]
	s_cmpk_lg_i32 s18, 0x600
	s_cbranch_scc1 .Lepi0_nograw
	v_bfe_u32 v195, v165, 6, 2
	v_cmp_eq_u32_e32 vcc, 0, v195
	s_and_saveexec_b64 s[8:9], vcc
	s_cbranch_execz .Lepi0_graw_done
	v_lshrrev_b32_e32 v195, 8, v165
	v_and_b32_e32 v196, 31, v165
	v_lshl_or_b32 v195, v195, 7, v196
	v_lshlrev_b32_e32 v195, 6, v195
	v_bfe_u32 v196, v165, 5, 1
	v_lshl_or_b32 v195, v196, 4, v195
	v_readlane_b32 s22, v250, 52
	v_readlane_b32 s23, v250, 53
	s_lshl_b32 s20, s17, 6
	s_add_u32 s22, s22, s20
	s_addc_u32 s23, s23, 0
	global_store_dwordx4 v195, v[114:117], s[22:23]
	global_store_dwordx4 v195, v[118:121], s[22:23] offset:32
	global_store_dwordx4 v195, v[82:85], s[22:23] offset:2048
	global_store_dwordx4 v195, v[86:89], s[22:23] offset:2080
	s_add_u32 s22, s22, 0x1000
	s_addc_u32 s23, s23, 0
	global_store_dwordx4 v195, v[50:53], s[22:23]
	global_store_dwordx4 v195, v[54:57], s[22:23] offset:32
	global_store_dwordx4 v195, v[18:21], s[22:23] offset:2048
	global_store_dwordx4 v195, v[22:25], s[22:23] offset:2080

; #define MFMA(a, b, c) __builtin_amdgcn_mfma_f32_32x32x16_bf16((a), (b), (c), 0, 0, 0)
; DI int crow(int reg, int h) { return (reg & 3) + 8 * (reg >> 2) + 4 * h; }
; template <int DQK>
; DI void attn_tile(const u16* __restrict__ q, int ldq, int qpos0, const Seg& s0, const Seg& s1, int nseg, bool has_sink,
;                   float sinkl2, u16* __restrict__ out, int ldo, char* lds) {
;     ...
;   auto compute = [&](int i) {
;     const Seg& sg = (i < nt0) ? s0 : s1;
;     const int off = ((i < nt0) ? i : i - nt0) << 6;
;     f32x16 sa = zero16(), sb = zero16();
; #pragma unroll
;     for (int ks = 0; ks < NKS; ++ks) {
;       bf16x8 a0 = *(const bf16x8*)(Ks + r * KST + ks * 16 + 8 * h);
;       bf16x8 a1 = *(const bf16x8*)(Ks + (32 + r) * KST + ks * 16 + 8 * h);
;       sa = MFMA(a0, qf[ks], sa);
;       sb = MFMA(a1, qf[ks], sb);
;     }
;     if (sg.masked) {
;       const int qpos = qpos0 + qi;
;       const int kb = sg.pos0 + off;
; #pragma unroll
;       for (int g = 0; g < 16; ++g) {
;         int d0 = kb + crow(g, h) - qpos, d1 = d0 + 32;
;         if (d0 > 128 || d0 < -128) sa[g] = -INFINITY;
;         if (d1 > 128 || d1 < -128) sb[g] = -INFINITY;
;       }
;     }
;     float mx = sa[0];
; #pragma unroll
;     for (int g = 1; g < 16; ++g) mx = fmaxf(mx, sa[g]);
; #pragma unroll
;     for (int g = 0; g < 16; ++g) mx = fmaxf(mx, sb[g]);
;     mx = fmaxf(mx, __shfl_xor(mx, 32));
;     const float mn = fmaxf(m, mx);
;     const float alpha = __builtin_amdgcn_exp2f(m - mn);
;     m = mn;
;     float ps = 0.f;
; #pragma unroll
;     for (int g = 0; g < 16; ++g) { sa[g] = __builtin_amdgcn_exp2f(sa[g] - mn); ps += sa[g]; }
; #pragma unroll
;     for (int g = 0; g < 16; ++g) { sb[g] = __builtin_amdgcn_exp2f(sb[g] - mn); ps += sb[g]; }
.LBB0_617:
	ds_read_b128 v[34:37], v130 offset:32768
	ds_read_b128 v[38:41], v130 offset:39424
	ds_read_b128 v[42:45], v130 offset:32800
	s_waitcnt lgkmcnt(2)
	v_mfma_f32_32x32x16_bf16 v[184:199], v[34:37], v[66:69], 0
	ds_read_b128 v[34:37], v130 offset:39456
	v_max3_f32 v137, v50, v51, v52
	v_max3_f32 v137, v137, v53, v54
	v_max3_f32 v137, v137, v55, v56
	v_max3_f32 v137, v137, v57, v58
	s_waitcnt lgkmcnt(2)
	v_mfma_f32_32x32x16_bf16 v[146:161], v[38:41], v[66:69], 0
	ds_read_b128 v[38:41], v130 offset:32832
	v_max3_f32 v137, v137, v59, v60
	v_max3_f32 v137, v137, v61, v62
	v_max3_f32 v137, v137, v63, v64
	v_max3_f32 v137, v137, v65, v218
	s_waitcnt lgkmcnt(2)
	v_mfma_f32_32x32x16_bf16 v[184:199], v[42:45], v[70:73], v[184:199]
	ds_read_b128 v[42:45], v130 offset:39488
	v_max3_f32 v137, v137, v219, v220
	v_max3_f32 v137, v137, v221, v222
	v_max3_f32 v137, v137, v223, v224
	v_max3_f32 v137, v137, v225, v226
	s_waitcnt lgkmcnt(2)
	v_mfma_f32_32x32x16_bf16 v[146:161], v[34:37], v[70:73], v[146:161]
	ds_read_b128 v[34:37], v130 offset:32864
	v_max3_f32 v137, v137, v227, v228
	v_max3_f32 v137, v137, v229, v230
	v_max3_f32 v137, v137, v231, v232
	v_max3_f32 v137, v137, v233, v233
	s_waitcnt lgkmcnt(2)
	v_mfma_f32_32x32x16_bf16 v[184:199], v[38:41], v[74:77], v[184:199]
	ds_read_b128 v[38:41], v130 offset:39520
	ds_bpermute_b32 v139, v131, v137
	s_waitcnt lgkmcnt(0)
	v_max3_f32 v135, v134, v137, v139
	v_sub_f32_e32 v141, v134, v135
	v_mfma_f32_32x32x16_bf16 v[146:161], v[42:45], v[74:77], v[146:161]
	ds_read_b128 v[42:45], v130 offset:32896
	v_exp_f32_e32 v140, v141
	v_mov_b32_e32 v144, v135
	v_mov_b32_e32 v145, v135
	v_sub_f32_e32 v50, v50, v135
	v_mfma_f32_32x32x16_bf16 v[184:199], v[34:37], v[78:81], v[184:199]
	ds_read_b128 v[34:37], v130 offset:39552
	v_sub_f32_e32 v51, v51, v135
	v_sub_f32_e32 v52, v52, v135
	v_sub_f32_e32 v53, v53, v135
	v_sub_f32_e32 v54, v54, v135
	v_mfma_f32_32x32x16_bf16 v[146:161], v[38:41], v[78:81], v[146:161]
	ds_read_b128 v[38:41], v130 offset:32928
	v_sub_f32_e32 v55, v55, v135
	v_sub_f32_e32 v56, v56, v135
	v_sub_f32_e32 v57, v57, v135
	v_exp_f32_e32 v50, v50
	s_waitcnt lgkmcnt(2)
	v_mfma_f32_32x32x16_bf16 v[184:199], v[42:45], v[82:85], v[184:199]
	ds_read_b128 v[42:45], v130 offset:39584
	v_sub_f32_e32 v58, v58, v135
	v_sub_f32_e32 v59, v59, v135
	v_sub_f32_e32 v60, v60, v135
	v_sub_f32_e32 v61, v61, v135
	s_waitcnt lgkmcnt(2)
	v_mfma_f32_32x32x16_bf16 v[146:161], v[34:37], v[82:85], v[146:161]
	v_exp_f32_e32 v51, v51
	v_sub_f32_e32 v62, v62, v135
	v_sub_f32_e32 v63, v63, v135
	v_sub_f32_e32 v64, v64, v135
	s_waitcnt lgkmcnt(1)
	v_mfma_f32_32x32x16_bf16 v[184:199], v[38:41], v[86:89], v[184:199]
	v_sub_f32_e32 v65, v65, v135
	v_exp_f32_e32 v52, v52
	v_sub_f32_e32 v218, v218, v135
	v_sub_f32_e32 v219, v219, v135
	s_waitcnt lgkmcnt(0)
	v_mfma_f32_32x32x16_bf16 v[146:161], v[42:45], v[86:89], v[146:161]
	ds_read_b64_tr_b16 v[46:47], v133 offset:13312
	ds_read_b64_tr_b16 v[48:49], v133 offset:14848
	ds_read_b64_tr_b16 v[200:201], v133 offset:13376
	ds_read_b64_tr_b16 v[202:203], v133 offset:14912
	ds_read_b64_tr_b16 v[204:205], v133 offset:16384
	ds_read_b64_tr_b16 v[206:207], v133 offset:17920
	v_sub_f32_e32 v220, v220, v135
	v_sub_f32_e32 v221, v221, v135
	v_exp_f32_e32 v53, v53
	v_sub_f32_e32 v222, v222, v135
	v_sub_f32_e32 v223, v223, v135
	v_sub_f32_e32 v224, v224, v135
	v_sub_f32_e32 v225, v225, v135
	v_exp_f32_e32 v54, v54
	v_mul_f32_e32 v33, v140, v33
	v_mul_f32_e32 v32, v140, v32
	v_mul_f32_e32 v31, v140, v31
	v_mul_f32_e32 v30, v140, v30
	v_exp_f32_e32 v55, v55
	v_mul_f32_e32 v29, v140, v29
	v_mul_f32_e32 v28, v140, v28
	v_mul_f32_e32 v27, v140, v27
	v_mul_f32_e32 v26, v140, v26
	v_exp_f32_e32 v56, v56
	v_mul_f32_e32 v25, v140, v25
	v_mul_f32_e32 v24, v140, v24
	v_mul_f32_e32 v23, v140, v23
	v_mul_f32_e32 v22, v140, v22
	v_exp_f32_e32 v57, v57
	v_mul_f32_e32 v21, v140, v21
	v_mul_f32_e32 v20, v140, v20
	v_mul_f32_e32 v19, v140, v19
	v_mul_f32_e32 v18, v140, v18
	v_exp_f32_e32 v58, v58
	v_sub_f32_e32 v226, v226, v135
	v_sub_f32_e32 v227, v227, v135
	v_sub_f32_e32 v228, v228, v135
	v_sub_f32_e32 v229, v229, v135
	v_sub_f32_e32 v230, v230, v135
	v_exp_f32_e32 v59, v59
	v_sub_f32_e32 v231, v231, v135
	v_sub_f32_e32 v232, v232, v135
	v_sub_f32_e32 v233, v233, v135
	v_mul_f32_e32 v17, v140, v17
	v_mul_f32_e32 v16, v140, v16
	v_exp_f32_e32 v60, v60
	v_mul_f32_e32 v15, v140, v15
	v_mul_f32_e32 v14, v140, v14
	v_mul_f32_e32 v13, v140, v13
	v_mul_f32_e32 v12, v140, v12
	v_mul_f32_e32 v11, v140, v11
	v_exp_f32_e32 v61, v61
	v_mul_f32_e32 v10, v140, v10
	v_mul_f32_e32 v9, v140, v9
	v_mul_f32_e32 v8, v140, v8
	v_mul_f32_e32 v7, v140, v7
	v_mul_f32_e32 v6, v140, v6
	v_exp_f32_e32 v62, v62
	v_mul_f32_e32 v5, v140, v5
	v_mul_f32_e32 v4, v140, v4
	v_mul_f32_e32 v3, v140, v3
	v_mul_f32_e32 v2, v140, v2
	v_add_f32_e32 v238, v50, v51
	v_exp_f32_e32 v63, v63
	v_add_f32_e32 v238, v238, v52
	v_add_f32_e32 v238, v238, v53
	v_add_f32_e32 v238, v238, v54
	v_add_f32_e32 v238, v238, v55
	v_add_f32_e32 v238, v238, v56
	v_exp_f32_e32 v64, v64
	v_add_f32_e32 v238, v238, v57
	v_cvt_pk_bf16_f32 v50, v50, v51
	v_cvt_pk_bf16_f32 v51, v52, v53
	v_cvt_pk_bf16_f32 v52, v54, v55
	v_cvt_pk_bf16_f32 v53, v56, v57
	v_exp_f32_e32 v65, v65
	s_nop 0
	s_waitcnt lgkmcnt(4)
; #define MFMA(a, b, c) __builtin_amdgcn_mfma_f32_32x32x16_bf16((a), (b), (c), 0, 0, 0)
; #define ATT_VTR(p) __builtin_bit_cast(s16x4, __builtin_amdgcn_ds_read_tr16_b64_v4i16((__attribute__((address_space(3))) v4i16_t*)(p)))
; template <int DQK>
; DI void attn_tile(const u16* __restrict__ q, int ldq, int qpos0, const Seg& s0, const Seg& s1, int nseg, bool has_sink,
;                   float sinkl2, u16* __restrict__ out, int ldo, char* lds) {
;     ...
;     l = l * alpha + ps;
; #pragma unroll
;     for (int g = 0; g < 16; ++g) { o0[g] *= alpha; o1[g] *= alpha; }
; #pragma unroll
;     for (int kt = 0; kt < 2; ++kt) {
; #pragma unroll
;       for (int s = 0; s < 2; ++s) {
;         const f32x16& sv = kt == 0 ? sa : sb;
;         uint4 pu;
;         pu.x = pack2(sv[8 * s + 0], sv[8 * s + 1]); pu.y = pack2(sv[8 * s + 2], sv[8 * s + 3]);
;         pu.z = pack2(sv[8 * s + 4], sv[8 * s + 5]); pu.w = pack2(sv[8 * s + 6], sv[8 * s + 7]);
;         bf16x8 pf = __builtin_bit_cast(bf16x8, pu);
;         const lds_cptr vp = vp0 + (kt * 32 + 16 * s) * (VST * 2);
;         {
;           s16x4 lo = ATT_VTR(vp);
;           s16x4 hi = ATT_VTR(vp + 8 * VST * 2);
;           bf16x8 vf = __builtin_shufflevector(lo, hi, 0, 1, 2, 3, 4, 5, 6, 7);
;           o0 = MFMA(vf, pf, o0);
;         }
;         {
;           s16x4 lo = ATT_VTR(vp + 64);
;           s16x4 hi = ATT_VTR(vp + 8 * VST * 2 + 64);
;           bf16x8 vf = __builtin_shufflevector(lo, hi, 0, 1, 2, 3, 4, 5, 6, 7);
;           o1 = MFMA(vf, pf, o1);
;         }
;       }
;     }
;   };
;   ATT_LOADX(0, kreg0, kreg1, vreg0);
;   ATT_LOADX(1, krgB0, krgB1, vrgB0);
;   for (int i = 0; i < NT; i += 2) {
;     __syncthreads();
;     ATT_STOREX(kreg0, kreg1, vreg0);
;     __syncthreads();
;     if (i + 2 < NT) ATT_LOADX(i + 2, kreg0, kreg1, vreg0);
;     compute(i);
;     __syncthreads();
;     ATT_STOREX(krgB0, krgB1, vrgB0);
;     __syncthreads();
;     if (i + 3 < NT) ATT_LOADX(i + 3, krgB0, krgB1, vrgB0);
;     compute(i + 1);
	v_mfma_f32_32x32x16_bf16 v[18:33], v[46:49], v[50:53], v[18:33]
	ds_read_b64_tr_b16 v[46:47], v133 offset:16448
	ds_read_b64_tr_b16 v[48:49], v133 offset:17984
	s_waitcnt lgkmcnt(4)
	v_mfma_f32_32x32x16_bf16 v[2:17], v[200:203], v[50:53], v[2:17]
	ds_read_b64_tr_b16 v[200:201], v133 offset:19456
	ds_read_b64_tr_b16 v[202:203], v133 offset:20992
	v_exp_f32_e32 v218, v218
	v_add_f32_e32 v238, v238, v58
	v_add_f32_e32 v238, v238, v59
	v_exp_f32_e32 v219, v219
	v_add_f32_e32 v238, v238, v60
	v_add_f32_e32 v238, v238, v61
	v_exp_f32_e32 v220, v220
	v_add_f32_e32 v238, v238, v62
	v_add_f32_e32 v238, v238, v63
	v_exp_f32_e32 v221, v221
	v_add_f32_e32 v238, v238, v64
	v_add_f32_e32 v238, v238, v65
	v_exp_f32_e32 v222, v222
	v_cvt_pk_bf16_f32 v54, v58, v59
	v_cvt_pk_bf16_f32 v55, v60, v61
	v_exp_f32_e32 v223, v223
	v_cvt_pk_bf16_f32 v56, v62, v63
	v_cvt_pk_bf16_f32 v57, v64, v65
	v_exp_f32_e32 v224, v224
	v_exp_f32_e32 v225, v225
	s_nop 0
	s_waitcnt lgkmcnt(4)
	v_mfma_f32_32x32x16_bf16 v[18:33], v[204:207], v[54:57], v[18:33]
	ds_read_b64_tr_b16 v[204:205], v133 offset:19520
	ds_read_b64_tr_b16 v[206:207], v133 offset:21056
	s_waitcnt lgkmcnt(4)
	v_mfma_f32_32x32x16_bf16 v[2:17], v[46:49], v[54:57], v[2:17]
	ds_read_b64_tr_b16 v[46:47], v133 offset:22528
	ds_read_b64_tr_b16 v[48:49], v133 offset:24064
	v_exp_f32_e32 v226, v226
	v_add_f32_e32 v238, v238, v218
	v_add_f32_e32 v238, v238, v219
	v_exp_f32_e32 v227, v227
	v_add_f32_e32 v238, v238, v220
	v_add_f32_e32 v238, v238, v221
	v_exp_f32_e32 v228, v228
	v_add_f32_e32 v238, v238, v222
	v_add_f32_e32 v238, v238, v223
	v_exp_f32_e32 v229, v229
	v_add_f32_e32 v238, v238, v224
	v_add_f32_e32 v238, v238, v225
	v_exp_f32_e32 v230, v230
	v_cvt_pk_bf16_f32 v218, v218, v219
	v_cvt_pk_bf16_f32 v219, v220, v221
	v_exp_f32_e32 v231, v231
	v_cvt_pk_bf16_f32 v220, v222, v223
	v_cvt_pk_bf16_f32 v221, v224, v225
	v_exp_f32_e32 v232, v232
	v_exp_f32_e32 v233, v233
	s_nop 0
	s_waitcnt lgkmcnt(4)
	v_mfma_f32_32x32x16_bf16 v[18:33], v[200:203], v[218:221], v[18:33]
	ds_read_b64_tr_b16 v[200:201], v133 offset:22592
	ds_read_b64_tr_b16 v[202:203], v133 offset:24128
	s_waitcnt lgkmcnt(4)
	v_mfma_f32_32x32x16_bf16 v[2:17], v[204:207], v[218:221], v[2:17]
	v_add_f32_e32 v238, v238, v226
	v_add_f32_e32 v238, v238, v227
	v_add_f32_e32 v238, v238, v228
	v_add_f32_e32 v238, v238, v229
	v_add_f32_e32 v238, v238, v230
	v_add_f32_e32 v238, v238, v231
	v_add_f32_e32 v238, v238, v232
	v_add_f32_e32 v238, v238, v233
	v_cvt_pk_bf16_f32 v222, v226, v227
	v_cvt_pk_bf16_f32 v223, v228, v229
	v_cvt_pk_bf16_f32 v224, v230, v231
	v_cvt_pk_bf16_f32 v225, v232, v233
	s_nop 0
	s_waitcnt lgkmcnt(2)
	v_mfma_f32_32x32x16_bf16 v[18:33], v[46:49], v[222:225], v[18:33]
	s_waitcnt lgkmcnt(0)
	v_mfma_f32_32x32x16_bf16 v[2:17], v[200:203], v[222:225], v[2:17]
	v_fma_f32 v136, v128, v140, v238
	s_waitcnt vmcnt(0)
	ds_write_b128 v121, v[90:93]
	s_and_saveexec_b64 s[4:5], s[0:1]
	ds_write_b128 v129, v[94:97]
	s_or_b64 exec, exec, s[4:5]
	s_cmp_gt_u32 s27, 64
	ds_write_b128 v132, v[110:113] offset:46080
	s_waitcnt lgkmcnt(0)
	s_barrier
	s_cbranch_scc1 .LBB0_602
	s_cmp_lt_u32 s27, 61
	s_cselect_b64 s[4:5], -1, 0
	s_and_b64 s[16:17], s[4:5], exec
	s_cselect_b32 s16, 0, 0x3ffffc0
	s_add_i32 s16, s16, s22
	s_lshl_b32 s28, s16, 6
	v_add_u32_e32 v36, s28, v116
	v_ashrrev_i32_e32 v37, 31, v36
	s_and_saveexec_b64 s[16:17], vcc
	s_xor_b64 s[16:17], exec, s[16:17]
	s_cbranch_execz .LBB0_623
	s_and_b64 s[18:19], s[4:5], exec
	s_cselect_b32 s19, s15, s11
	s_cselect_b32 s18, s14, s10
	v_lshlrev_b64 v[36:37], 6, v[36:37]
	v_lshl_add_u64 v[36:37], s[18:19], 0, v[36:37]
	s_movk_i32 s18, 0xff80
	v_lshl_add_u64 v[36:37], v[124:125], 1, v[36:37]
	s_mov_b32 s19, -1
	v_lshl_add_u64 v[38:39], v[36:37], 0, s[18:19]
	s_andn2_saveexec_b64 s[16:17], s[16:17]
	s_cbranch_execnz .LBB0_624

; #define G5_LOAD(k0)                                                                 \
;   {                                                                                 \
;     _Pragma("unroll") for (int i_ = 0; i_ < 4; ++i_) ra[i_] = ldg16(Ap + (size_t)(i_ * 64) * lda + (k0)); \
;     _Pragma("unroll") for (int i_ = 0; i_ < 4; ++i_) rb[i_] = ldg16(Bp + (size_t)(i_ * 64) * ldb + (k0)); \
;   }
; #define G5_STORE(s)                                                                 \
;   {                                                                                 \
;     _Pragma("unroll") for (int i_ = 0; i_ < 4; ++i_) *(u32x4*)(Sw + (s) * STG + i_ * 64 * GS) = ra[i_]; \
;     _Pragma("unroll") for (int i_ = 0; i_ < 4; ++i_) *(u32x4*)(Sw + (s) * STG + 256 * GS + i_ * 64 * GS) = rb[i_]; \
;   }
; template <typename Epi>
; DI void gemm_tile512(const u16* __restrict__ A, int lda, const u16* __restrict__ Bt, int ldb, int K, char* lds_all, Epi epi) {
;     ...
;   const int nk = K >> 6;
;   __syncthreads();
;   G5_LOAD(0);
;   G5_STORE(0);
;   G5_LOAD(64);
;   __syncthreads();
;   for (int kt = 0; kt + 2 < nk; ++kt) {
;     const int cur = kt & 1;
;     G5_COMPUTE(cur);
;     G5_STORE(cur ^ 1);
;     G5_LOAD((kt + 2) << 6);
;     __syncthreads();
;   }
.Lg3_k_m2:
	s_barrier
	ds_read_b128 v[194:197], v179 offset:36864
	ds_read_b128 v[166:169], v178
	ds_read_b128 v[198:201], v179 offset:41472
	ds_read_b128 v[170:173], v178 offset:4608
	ds_read_b128 v[174:177], v178 offset:9216
	ds_read_b128 v[190:193], v178 offset:13824
	s_waitcnt lgkmcnt(4)
	v_mfma_f32_32x32x16_bf16 v[114:129], v[194:197], v[166:169], 0
	ds_read_b128 v[234:237], v179 offset:36896
	s_waitcnt lgkmcnt(4)
	v_mfma_f32_32x32x16_bf16 v[98:113], v[198:201], v[166:169], 0
	ds_read_b128 v[218:221], v178 offset:32
	s_waitcnt lgkmcnt(4)
	v_mfma_f32_32x32x16_bf16 v[82:97], v[194:197], v[170:173], 0
	ds_read_b128 v[202:205], v179 offset:41504
	v_mfma_f32_32x32x16_bf16 v[66:81], v[198:201], v[170:173], 0
	ds_read_b128 v[222:225], v178 offset:4640
	global_load_dwordx4 v[130:133], v206, s[98:99]
	s_waitcnt lgkmcnt(5)
	v_mfma_f32_32x32x16_bf16 v[50:65], v[194:197], v[174:177], 0
	ds_read_b128 v[226:229], v178 offset:9248
	v_mfma_f32_32x32x16_bf16 v[34:49], v[198:201], v[174:177], 0
	ds_read_b128 v[230:233], v178 offset:13856
	s_waitcnt lgkmcnt(6)
	v_mfma_f32_32x32x16_bf16 v[18:33], v[194:197], v[190:193], 0
	v_mfma_f32_32x32x16_bf16 v[2:17], v[198:201], v[190:193], 0
	global_load_dwordx4 v[134:137], v207, s[98:99]
	s_waitcnt lgkmcnt(4)
	v_mfma_f32_32x32x16_bf16 v[114:129], v[234:237], v[218:221], v[114:129]
	ds_read_b128 v[194:197], v179 offset:36928
	s_waitcnt lgkmcnt(4)
	v_mfma_f32_32x32x16_bf16 v[98:113], v[202:205], v[218:221], v[98:113]
	ds_read_b128 v[166:169], v178 offset:64
	s_waitcnt lgkmcnt(4)
	v_mfma_f32_32x32x16_bf16 v[82:97], v[234:237], v[222:225], v[82:97]
	ds_read_b128 v[198:201], v179 offset:41536
	v_mfma_f32_32x32x16_bf16 v[66:81], v[202:205], v[222:225], v[66:81]
	ds_read_b128 v[170:173], v178 offset:4672
	global_load_dwordx4 v[138:141], v208, s[98:99]
	s_waitcnt lgkmcnt(5)
	v_mfma_f32_32x32x16_bf16 v[50:65], v[234:237], v[226:229], v[50:65]
	ds_read_b128 v[174:177], v178 offset:9280
	v_mfma_f32_32x32x16_bf16 v[34:49], v[202:205], v[226:229], v[34:49]
	ds_read_b128 v[190:193], v178 offset:13888
	s_waitcnt lgkmcnt(6)
	v_mfma_f32_32x32x16_bf16 v[18:33], v[234:237], v[230:233], v[18:33]
	v_mfma_f32_32x32x16_bf16 v[2:17], v[202:205], v[230:233], v[2:17]
	global_load_dwordx4 v[142:145], v238, s[98:99]
	s_waitcnt lgkmcnt(4)
	v_mfma_f32_32x32x16_bf16 v[114:129], v[194:197], v[166:169], v[114:129]
	ds_read_b128 v[234:237], v179 offset:36960
	s_waitcnt lgkmcnt(4)
	v_mfma_f32_32x32x16_bf16 v[98:113], v[198:201], v[166:169], v[98:113]
	ds_read_b128 v[218:221], v178 offset:96
	global_load_dwordx4 v[146:149], v206, s[100:101]
	s_waitcnt lgkmcnt(4)
	v_mfma_f32_32x32x16_bf16 v[82:97], v[194:197], v[170:173], v[82:97]
	ds_read_b128 v[202:205], v179 offset:41568
	v_mfma_f32_32x32x16_bf16 v[66:81], v[198:201], v[170:173], v[66:81]
	ds_read_b128 v[222:225], v178 offset:4704
	global_load_dwordx4 v[150:153], v207, s[100:101]
	s_waitcnt lgkmcnt(5)
	v_mfma_f32_32x32x16_bf16 v[50:65], v[194:197], v[174:177], v[50:65]
	ds_read_b128 v[226:229], v178 offset:9312
	v_mfma_f32_32x32x16_bf16 v[34:49], v[198:201], v[174:177], v[34:49]
	ds_read_b128 v[230:233], v178 offset:13920
	global_load_dwordx4 v[154:157], v208, s[100:101]
	v_add_u32_e32 v178, s11, v178
	v_add_u32_e32 v179, s11, v179
	s_waitcnt lgkmcnt(6)
	v_mfma_f32_32x32x16_bf16 v[18:33], v[194:197], v[190:193], v[18:33]
	v_mfma_f32_32x32x16_bf16 v[2:17], v[198:201], v[190:193], v[2:17]
	global_load_dwordx4 v[158:161], v238, s[100:101]
	v_subrev_u32_e32 v180, s11, v180
	s_sub_u32 s11, 0, s11
	s_add_u32 s98, s98, 0x80
	s_addc_u32 s99, s99, 0
	s_add_u32 s100, s100, 0x80
	s_addc_u32 s101, s101, 0
	s_waitcnt lgkmcnt(0)
.Lg3_loop_m2:
	s_barrier
	ds_read_b128 v[194:197], v179 offset:36864
	ds_read_b128 v[166:169], v178
	v_mfma_f32_32x32x16_bf16 v[114:129], v[234:237], v[218:221], v[114:129]
	ds_read_b128 v[198:201], v179 offset:41472
	v_mfma_f32_32x32x16_bf16 v[98:113], v[202:205], v[218:221], v[98:113]
	ds_read_b128 v[170:173], v178 offset:4608
	v_mfma_f32_32x32x16_bf16 v[82:97], v[234:237], v[222:225], v[82:97]
	ds_read_b128 v[174:177], v178 offset:9216
	v_mfma_f32_32x32x16_bf16 v[66:81], v[202:205], v[222:225], v[66:81]
	ds_read_b128 v[190:193], v178 offset:13824
	v_mfma_f32_32x32x16_bf16 v[50:65], v[234:237], v[226:229], v[50:65]
	v_mfma_f32_32x32x16_bf16 v[34:49], v[202:205], v[226:229], v[34:49]
	v_mfma_f32_32x32x16_bf16 v[18:33], v[234:237], v[230:233], v[18:33]
	v_mfma_f32_32x32x16_bf16 v[2:17], v[202:205], v[230:233], v[2:17]
	s_waitcnt lgkmcnt(4)
	v_mfma_f32_32x32x16_bf16 v[114:129], v[194:197], v[166:169], v[114:129]
	ds_read_b128 v[234:237], v179 offset:36896
	s_waitcnt lgkmcnt(4)
	v_mfma_f32_32x32x16_bf16 v[98:113], v[198:201], v[166:169], v[98:113]
	ds_read_b128 v[218:221], v178 offset:32
	s_waitcnt lgkmcnt(4)
	v_mfma_f32_32x32x16_bf16 v[82:97], v[194:197], v[170:173], v[82:97]
	ds_read_b128 v[202:205], v179 offset:41504
	v_mfma_f32_32x32x16_bf16 v[66:81], v[198:201], v[170:173], v[66:81]
	ds_read_b128 v[222:225], v178 offset:4640
	s_waitcnt vmcnt(7)
	ds_write_b128 v180, v[130:133]
	global_load_dwordx4 v[130:133], v206, s[98:99]
	s_waitcnt lgkmcnt(6)
	v_mfma_f32_32x32x16_bf16 v[50:65], v[194:197], v[174:177], v[50:65]
	ds_read_b128 v[226:229], v178 offset:9248
	v_mfma_f32_32x32x16_bf16 v[34:49], v[198:201], v[174:177], v[34:49]
	ds_read_b128 v[230:233], v178 offset:13856
	s_waitcnt lgkmcnt(7)
	v_mfma_f32_32x32x16_bf16 v[18:33], v[194:197], v[190:193], v[18:33]
	v_mfma_f32_32x32x16_bf16 v[2:17], v[198:201], v[190:193], v[2:17]
	s_waitcnt vmcnt(7)
	ds_write_b128 v180, v[134:137] offset:9216
	global_load_dwordx4 v[134:137], v207, s[98:99]
	s_waitcnt lgkmcnt(6)
; #define G5_LOAD(k0)                                                                 \
;   {                                                                                 \
;     _Pragma("unroll") for (int i_ = 0; i_ < 4; ++i_) ra[i_] = ldg16(Ap + (size_t)(i_ * 64) * lda + (k0)); \
;     _Pragma("unroll") for (int i_ = 0; i_ < 4; ++i_) rb[i_] = ldg16(Bp + (size_t)(i_ * 64) * ldb + (k0)); \
;   }
; #define G5_STORE(s)                                                                 \
;   {                                                                                 \
;     _Pragma("unroll") for (int i_ = 0; i_ < 4; ++i_) *(u32x4*)(Sw + (s) * STG + i_ * 64 * GS) = ra[i_]; \
;     _Pragma("unroll") for (int i_ = 0; i_ < 4; ++i_) *(u32x4*)(Sw + (s) * STG + 256 * GS + i_ * 64 * GS) = rb[i_]; \
;   }
; template <typename Epi>
; DI void gemm_tile512(const u16* __restrict__ A, int lda, const u16* __restrict__ Bt, int ldb, int K, char* lds_all, Epi epi) {
;     ...
;   const int nk = K >> 6;
;   __syncthreads();
;   G5_LOAD(0);
;   G5_STORE(0);
;   G5_LOAD(64);
;   __syncthreads();
;   for (int kt = 0; kt + 2 < nk; ++kt) {
;     const int cur = kt & 1;
;     G5_COMPUTE(cur);
;     G5_STORE(cur ^ 1);
;     G5_LOAD((kt + 2) << 6);
;     __syncthreads();
;   }
	v_mfma_f32_32x32x16_bf16 v[114:129], v[234:237], v[218:221], v[114:129]
	ds_read_b128 v[194:197], v179 offset:36928
	s_waitcnt lgkmcnt(6)
	v_mfma_f32_32x32x16_bf16 v[98:113], v[202:205], v[218:221], v[98:113]
	ds_read_b128 v[166:169], v178 offset:64
	s_waitcnt lgkmcnt(6)
	v_mfma_f32_32x32x16_bf16 v[82:97], v[234:237], v[222:225], v[82:97]
	ds_read_b128 v[198:201], v179 offset:41536
	v_mfma_f32_32x32x16_bf16 v[66:81], v[202:205], v[222:225], v[66:81]
	ds_read_b128 v[170:173], v178 offset:4672
	s_waitcnt vmcnt(7)
	ds_write_b128 v180, v[138:141] offset:18432
	global_load_dwordx4 v[138:141], v208, s[98:99]
	s_waitcnt lgkmcnt(7)
	v_mfma_f32_32x32x16_bf16 v[50:65], v[234:237], v[226:229], v[50:65]
	ds_read_b128 v[174:177], v178 offset:9280
	v_mfma_f32_32x32x16_bf16 v[34:49], v[202:205], v[226:229], v[34:49]
	ds_read_b128 v[190:193], v178 offset:13888
	s_waitcnt lgkmcnt(8)
	v_mfma_f32_32x32x16_bf16 v[18:33], v[234:237], v[230:233], v[18:33]
	v_mfma_f32_32x32x16_bf16 v[2:17], v[202:205], v[230:233], v[2:17]
	s_waitcnt vmcnt(7)
	ds_write_b128 v180, v[142:145] offset:27648
	global_load_dwordx4 v[142:145], v238, s[98:99]
	s_waitcnt lgkmcnt(6)
	v_mfma_f32_32x32x16_bf16 v[114:129], v[194:197], v[166:169], v[114:129]
	ds_read_b128 v[234:237], v179 offset:36960
	s_waitcnt lgkmcnt(6)
	v_mfma_f32_32x32x16_bf16 v[98:113], v[198:201], v[166:169], v[98:113]
	ds_read_b128 v[218:221], v178 offset:96
	s_waitcnt vmcnt(7)
	ds_write_b128 v180, v[146:149] offset:36864
	global_load_dwordx4 v[146:149], v206, s[100:101]
	s_waitcnt lgkmcnt(7)
	v_mfma_f32_32x32x16_bf16 v[82:97], v[194:197], v[170:173], v[82:97]
	ds_read_b128 v[202:205], v179 offset:41568
	v_mfma_f32_32x32x16_bf16 v[66:81], v[198:201], v[170:173], v[66:81]
	ds_read_b128 v[222:225], v178 offset:4704
	s_waitcnt vmcnt(7)
	ds_write_b128 v180, v[150:153] offset:46080
	global_load_dwordx4 v[150:153], v207, s[100:101]
	s_waitcnt lgkmcnt(8)
	v_mfma_f32_32x32x16_bf16 v[50:65], v[194:197], v[174:177], v[50:65]
	ds_read_b128 v[226:229], v178 offset:9312
	v_mfma_f32_32x32x16_bf16 v[34:49], v[198:201], v[174:177], v[34:49]
	ds_read_b128 v[230:233], v178 offset:13920
	s_waitcnt vmcnt(7)
	ds_write_b128 v180, v[154:157] offset:55296
	global_load_dwordx4 v[154:157], v208, s[100:101]
	v_add_u32_e32 v178, s11, v178
	v_add_u32_e32 v179, s11, v179
	s_waitcnt lgkmcnt(10)
	v_mfma_f32_32x32x16_bf16 v[18:33], v[194:197], v[190:193], v[18:33]
	v_mfma_f32_32x32x16_bf16 v[2:17], v[198:201], v[190:193], v[2:17]
	s_waitcnt vmcnt(7)
	ds_write_b128 v180, v[158:161] offset:64512
	global_load_dwordx4 v[158:161], v238, s[100:101]
	v_subrev_u32_e32 v180, s11, v180
	s_sub_u32 s11, 0, s11
	s_add_u32 s98, s98, 0x80
	s_addc_u32 s99, s99, 0
	s_add_u32 s100, s100, 0x80
	s_addc_u32 s101, s101, 0
	s_waitcnt lgkmcnt(0)
	s_sub_u32 s12, s12, 1
	s_cmp_lg_u32 s12, 0
	s_cbranch_scc1 .Lg3_loop_m2
	s_barrier
	ds_read_b128 v[194:197], v179 offset:36864
	ds_read_b128 v[166:169], v178
	v_mfma_f32_32x32x16_bf16 v[114:129], v[234:237], v[218:221], v[114:129]
	ds_read_b128 v[198:201], v179 offset:41472
	v_mfma_f32_32x32x16_bf16 v[98:113], v[202:205], v[218:221], v[98:113]
	ds_read_b128 v[170:173], v178 offset:4608
	v_mfma_f32_32x32x16_bf16 v[82:97], v[234:237], v[222:225], v[82:97]
	ds_read_b128 v[174:177], v178 offset:9216
	v_mfma_f32_32x32x16_bf16 v[66:81], v[202:205], v[222:225], v[66:81]
	ds_read_b128 v[190:193], v178 offset:13824
	v_mfma_f32_32x32x16_bf16 v[50:65], v[234:237], v[226:229], v[50:65]
	v_mfma_f32_32x32x16_bf16 v[34:49], v[202:205], v[226:229], v[34:49]
	v_mfma_f32_32x32x16_bf16 v[18:33], v[234:237], v[230:233], v[18:33]
	v_mfma_f32_32x32x16_bf16 v[2:17], v[202:205], v[230:233], v[2:17]
	s_waitcnt lgkmcnt(4)
	v_mfma_f32_32x32x16_bf16 v[114:129], v[194:197], v[166:169], v[114:129]
	ds_read_b128 v[234:237], v179 offset:36896
	s_waitcnt lgkmcnt(4)
	v_mfma_f32_32x32x16_bf16 v[98:113], v[198:201], v[166:169], v[98:113]
	ds_read_b128 v[218:221], v178 offset:32
	s_waitcnt lgkmcnt(4)
	v_mfma_f32_32x32x16_bf16 v[82:97], v[194:197], v[170:173], v[82:97]
	ds_read_b128 v[202:205], v179 offset:41504
	v_mfma_f32_32x32x16_bf16 v[66:81], v[198:201], v[170:173], v[66:81]
	ds_read_b128 v[222:225], v178 offset:4640
	s_waitcnt vmcnt(7)
	ds_write_b128 v180, v[130:133]
	s_waitcnt lgkmcnt(6)
	v_mfma_f32_32x32x16_bf16 v[50:65], v[194:197], v[174:177], v[50:65]
	ds_read_b128 v[226:229], v178 offset:9248
	v_mfma_f32_32x32x16_bf16 v[34:49], v[198:201], v[174:177], v[34:49]
	ds_read_b128 v[230:233], v178 offset:13856
	s_waitcnt lgkmcnt(7)
	v_mfma_f32_32x32x16_bf16 v[18:33], v[194:197], v[190:193], v[18:33]
	v_mfma_f32_32x32x16_bf16 v[2:17], v[198:201], v[190:193], v[2:17]
	s_waitcnt vmcnt(6)
	ds_write_b128 v180, v[134:137] offset:9216
	s_waitcnt lgkmcnt(6)
	v_mfma_f32_32x32x16_bf16 v[114:129], v[234:237], v[218:221], v[114:129]
	ds_read_b128 v[194:197], v179 offset:36928
	s_waitcnt lgkmcnt(6)
	v_mfma_f32_32x32x16_bf16 v[98:113], v[202:205], v[218:221], v[98:113]
	ds_read_b128 v[166:169], v178 offset:64
	s_waitcnt lgkmcnt(6)
	v_mfma_f32_32x32x16_bf16 v[82:97], v[234:237], v[222:225], v[82:97]
	ds_read_b128 v[198:201], v179 offset:41536
	v_mfma_f32_32x32x16_bf16 v[66:81], v[202:205], v[222:225], v[66:81]
	ds_read_b128 v[170:173], v178 offset:4672
	s_waitcnt vmcnt(5)
	ds_write_b128 v180, v[138:141] offset:18432
	s_waitcnt lgkmcnt(7)
	v_mfma_f32_32x32x16_bf16 v[50:65], v[234:237], v[226:229], v[50:65]
	ds_read_b128 v[174:177], v178 offset:9280
	v_mfma_f32_32x32x16_bf16 v[34:49], v[202:205], v[226:229], v[34:49]
	ds_read_b128 v[190:193], v178 offset:13888
	s_waitcnt lgkmcnt(8)
	v_mfma_f32_32x32x16_bf16 v[18:33], v[234:237], v[230:233], v[18:33]
	v_mfma_f32_32x32x16_bf16 v[2:17], v[202:205], v[230:233], v[2:17]
	s_waitcnt vmcnt(4)
; #define G5_STORE(s)                                                                 \
;   {                                                                                 \
;     _Pragma("unroll") for (int i_ = 0; i_ < 4; ++i_) *(u32x4*)(Sw + (s) * STG + i_ * 64 * GS) = ra[i_]; \
;     _Pragma("unroll") for (int i_ = 0; i_ < 4; ++i_) *(u32x4*)(Sw + (s) * STG + 256 * GS + i_ * 64 * GS) = rb[i_]; \
;   }
; template <typename Epi>
; DI void gemm_tile512(const u16* __restrict__ A, int lda, const u16* __restrict__ Bt, int ldb, int K, char* lds_all, Epi epi) {
;     ...
;   {
;     const int cur = (nk - 2) & 1;
;     G5_COMPUTE(cur);
;     G5_STORE(cur ^ 1);
;     __syncthreads();
;     G5_COMPUTE(cur ^ 1);
;   }
; DI void gemm_phase(const Params& p, int layer, int mode, int nrows, char* lds_all) {
;     ...
;   for (int i = jb;; i += nj) {
;     const int srl = i / per, rem = i - srl * per;
;     const int sr = xcd + nx * srl;
;     if (sr >= nsr) break;
;     const int tn = rem >> 1, tm = sr * 2 + (rem & 1);
;     const int m0 = tm * 256, n0 = tn * 256;
	ds_write_b128 v180, v[142:145] offset:27648
	s_waitcnt lgkmcnt(6)
	v_mfma_f32_32x32x16_bf16 v[114:129], v[194:197], v[166:169], v[114:129]
	ds_read_b128 v[234:237], v179 offset:36960
	s_waitcnt lgkmcnt(6)
	v_mfma_f32_32x32x16_bf16 v[98:113], v[198:201], v[166:169], v[98:113]
	ds_read_b128 v[218:221], v178 offset:96
	s_waitcnt vmcnt(3)
	ds_write_b128 v180, v[146:149] offset:36864
	s_waitcnt lgkmcnt(7)
	v_mfma_f32_32x32x16_bf16 v[82:97], v[194:197], v[170:173], v[82:97]
	ds_read_b128 v[202:205], v179 offset:41568
	v_mfma_f32_32x32x16_bf16 v[66:81], v[198:201], v[170:173], v[66:81]
	ds_read_b128 v[222:225], v178 offset:4704
	s_waitcnt vmcnt(2)
	ds_write_b128 v180, v[150:153] offset:46080
	s_waitcnt lgkmcnt(8)
	v_mfma_f32_32x32x16_bf16 v[50:65], v[194:197], v[174:177], v[50:65]
	ds_read_b128 v[226:229], v178 offset:9312
	v_mfma_f32_32x32x16_bf16 v[34:49], v[198:201], v[174:177], v[34:49]
	ds_read_b128 v[230:233], v178 offset:13920
	s_waitcnt vmcnt(1)
	ds_write_b128 v180, v[154:157] offset:55296
	v_add_u32_e32 v178, s11, v178
	v_add_u32_e32 v179, s11, v179
	s_waitcnt lgkmcnt(10)
	v_mfma_f32_32x32x16_bf16 v[18:33], v[194:197], v[190:193], v[18:33]
	v_mfma_f32_32x32x16_bf16 v[2:17], v[198:201], v[190:193], v[2:17]
	s_waitcnt vmcnt(0)
	ds_write_b128 v180, v[158:161] offset:64512
	v_subrev_u32_e32 v180, s11, v180
	s_sub_u32 s11, 0, s11
	s_add_u32 s98, s98, 0x80
	s_addc_u32 s99, s99, 0
	s_add_u32 s100, s100, 0x80
	s_addc_u32 s101, s101, 0
	s_waitcnt lgkmcnt(0)
	s_barrier
	ds_read_b128 v[194:197], v179 offset:36864
	ds_read_b128 v[166:169], v178
	v_mfma_f32_32x32x16_bf16 v[114:129], v[234:237], v[218:221], v[114:129]
	ds_read_b128 v[198:201], v179 offset:41472
	v_mfma_f32_32x32x16_bf16 v[98:113], v[202:205], v[218:221], v[98:113]
	ds_read_b128 v[170:173], v178 offset:4608
	v_mfma_f32_32x32x16_bf16 v[82:97], v[234:237], v[222:225], v[82:97]
	ds_read_b128 v[174:177], v178 offset:9216
	v_mfma_f32_32x32x16_bf16 v[66:81], v[202:205], v[222:225], v[66:81]
	ds_read_b128 v[190:193], v178 offset:13824
	v_mfma_f32_32x32x16_bf16 v[50:65], v[234:237], v[226:229], v[50:65]
	v_mfma_f32_32x32x16_bf16 v[34:49], v[202:205], v[226:229], v[34:49]
	v_mfma_f32_32x32x16_bf16 v[18:33], v[234:237], v[230:233], v[18:33]
	v_mfma_f32_32x32x16_bf16 v[2:17], v[202:205], v[230:233], v[2:17]
	s_waitcnt lgkmcnt(4)
	v_mfma_f32_32x32x16_bf16 v[114:129], v[194:197], v[166:169], v[114:129]
	ds_read_b128 v[234:237], v179 offset:36896
	s_waitcnt lgkmcnt(4)
	v_mfma_f32_32x32x16_bf16 v[98:113], v[198:201], v[166:169], v[98:113]
	ds_read_b128 v[218:221], v178 offset:32
	s_waitcnt lgkmcnt(4)
	v_mfma_f32_32x32x16_bf16 v[82:97], v[194:197], v[170:173], v[82:97]
	ds_read_b128 v[202:205], v179 offset:41504
	v_mfma_f32_32x32x16_bf16 v[66:81], v[198:201], v[170:173], v[66:81]
	ds_read_b128 v[222:225], v178 offset:4640
	s_waitcnt lgkmcnt(5)
	v_mfma_f32_32x32x16_bf16 v[50:65], v[194:197], v[174:177], v[50:65]
	ds_read_b128 v[226:229], v178 offset:9248
	v_mfma_f32_32x32x16_bf16 v[34:49], v[198:201], v[174:177], v[34:49]
	ds_read_b128 v[230:233], v178 offset:13856
	s_waitcnt lgkmcnt(6)
	v_mfma_f32_32x32x16_bf16 v[18:33], v[194:197], v[190:193], v[18:33]
	v_mfma_f32_32x32x16_bf16 v[2:17], v[198:201], v[190:193], v[2:17]
	s_waitcnt lgkmcnt(4)
	v_mfma_f32_32x32x16_bf16 v[114:129], v[234:237], v[218:221], v[114:129]
	ds_read_b128 v[194:197], v179 offset:36928
	s_waitcnt lgkmcnt(4)
	v_mfma_f32_32x32x16_bf16 v[98:113], v[202:205], v[218:221], v[98:113]
	ds_read_b128 v[166:169], v178 offset:64
	s_waitcnt lgkmcnt(4)
	v_mfma_f32_32x32x16_bf16 v[82:97], v[234:237], v[222:225], v[82:97]
	ds_read_b128 v[198:201], v179 offset:41536
	v_mfma_f32_32x32x16_bf16 v[66:81], v[202:205], v[222:225], v[66:81]
	ds_read_b128 v[170:173], v178 offset:4672
	s_waitcnt lgkmcnt(5)
	v_mfma_f32_32x32x16_bf16 v[50:65], v[234:237], v[226:229], v[50:65]
	ds_read_b128 v[174:177], v178 offset:9280
	v_mfma_f32_32x32x16_bf16 v[34:49], v[202:205], v[226:229], v[34:49]
	ds_read_b128 v[190:193], v178 offset:13888
	s_waitcnt lgkmcnt(6)
	v_mfma_f32_32x32x16_bf16 v[18:33], v[234:237], v[230:233], v[18:33]
	v_mfma_f32_32x32x16_bf16 v[2:17], v[202:205], v[230:233], v[2:17]
	s_waitcnt lgkmcnt(4)
	v_mfma_f32_32x32x16_bf16 v[114:129], v[194:197], v[166:169], v[114:129]
	ds_read_b128 v[234:237], v179 offset:36960
	s_waitcnt lgkmcnt(4)
	v_mfma_f32_32x32x16_bf16 v[98:113], v[198:201], v[166:169], v[98:113]
	ds_read_b128 v[218:221], v178 offset:96
	s_waitcnt lgkmcnt(4)
	v_mfma_f32_32x32x16_bf16 v[82:97], v[194:197], v[170:173], v[82:97]
	ds_read_b128 v[202:205], v179 offset:41568
	v_mfma_f32_32x32x16_bf16 v[66:81], v[198:201], v[170:173], v[66:81]
	ds_read_b128 v[222:225], v178 offset:4704
	s_waitcnt lgkmcnt(5)
	v_mfma_f32_32x32x16_bf16 v[50:65], v[194:197], v[174:177], v[50:65]
	ds_read_b128 v[226:229], v178 offset:9312
	v_mfma_f32_32x32x16_bf16 v[34:49], v[198:201], v[174:177], v[34:49]
	ds_read_b128 v[230:233], v178 offset:13920
	s_waitcnt lgkmcnt(6)
	v_mfma_f32_32x32x16_bf16 v[18:33], v[194:197], v[190:193], v[18:33]
	v_mfma_f32_32x32x16_bf16 v[2:17], v[198:201], v[190:193], v[2:17]
	s_waitcnt lgkmcnt(0)
	v_mfma_f32_32x32x16_bf16 v[114:129], v[234:237], v[218:221], v[114:129]
	v_mfma_f32_32x32x16_bf16 v[98:113], v[202:205], v[218:221], v[98:113]
	v_mfma_f32_32x32x16_bf16 v[82:97], v[234:237], v[222:225], v[82:97]
	v_mfma_f32_32x32x16_bf16 v[66:81], v[202:205], v[222:225], v[66:81]
	v_mfma_f32_32x32x16_bf16 v[50:65], v[234:237], v[226:229], v[50:65]
	v_mfma_f32_32x32x16_bf16 v[34:49], v[202:205], v[226:229], v[34:49]
	v_mfma_f32_32x32x16_bf16 v[18:33], v[234:237], v[230:233], v[18:33]
	v_mfma_f32_32x32x16_bf16 v[2:17], v[202:205], v[230:233], v[2:17]
	s_mul_i32 s10, s22, 0x2100
	s_lshl_b32 s20, s23, 1
	s_add_u32 s10, s10, s20
	v_lshrrev_b32_e32 v237, 5, v165
	v_and_b32_e32 v194, 31, v165
	v_mul_u32_u24_e32 v234, 0x2100, v237
	v_lshl_add_u32 v234, v194, 4, v234
	v_add_u32_e32 v234, s10, v234
	s_add_i32 s21, s21, s18
	s_ashr_i32 s4, s21, 31
	s_lshr_b32 s4, s4, 27
	s_add_i32 s4, s21, s4
	s_ashr_i32 s4, s4, 5
	v_readlane_b32 s5, v252, 2
	v_readlane_b32 s8, v252, 6
	s_lshl_b32 s5, s4, s5
	s_add_i32 s17, s17, s8
	v_readlane_b32 s8, v252, 9
	s_add_i32 s5, s5, s19
	s_add_i32 s16, s16, s8
	s_cmp_lt_i32 s5, s36
	s_cselect_b32 s10, 1, 0
	s_cmp_eq_u32 s10, 0
	s_cbranch_scc1 .Lg3_nonext_m2
	s_lshl_b32 s24, s4, 5
	s_sub_i32 s24, s21, s24
	s_xor_b32 s11, s4, 1
	s_lshl_b32 s11, s11, 3
	s_add_i32 s11, s11, s19
	s_cmp_lt_i32 s11, s36
	s_cbranch_scc0 .Lm2map_old_b
	s_and_b32 s11, s4, 0xfffffffe
	s_bfe_u32 s5, s24, 0x10001
	s_add_i32 s11, s11, s5
	s_lshl_b32 s11, s11, 3
	s_add_i32 s11, s11, s19
	s_lshl_b32 s11, s11, 9
	s_and_b32 s5, s24, 1
	s_lshl_b32 s5, s5, 8
	s_or_b32 s22, s11, s5
	s_lshr_b32 s23, s24, 2
	s_and_b32 s5, s4, 1
	s_lshl_b32 s5, s5, 3
	s_add_i32 s23, s23, s5
	s_lshl_b32 s23, s23, 8
	s_branch .Lm2map_done_b
